# older waves 0-3 issue the LDS-DMA pieces of their SIMD partners in the diff-attention loop, plus progress-based s_setprio 3,2,1,0 per step
# speedup vs baseline: 1.0053x; 1.0053x over previous
; #define LAS __attribute__((address_space(3)))
; DI void attn_step32(f32x16& sc, f32x16& sn, f32x16 (&O)[4], const f32x16& negm, float& lsum, float& mrun, const bf16x8 (&qf)[4],
;                     bf16x8 (&kf)[4], const LAS unsigned char* kb_next, bool has_next, const LAS unsigned char* vb, const int (&ko)[4], int vo0, int vo1) {
;     bf16x8 vf[8];
; #pragma unroll
;     for (int cb = 0; cb < 4; ++cb) { vf[cb] = *(const LAS bf16x8*)(vb + vo0 + cb * 4096); vf[4 + cb] = *(const LAS bf16x8*)(vb + vo1 + cb * 4096); }
;     __builtin_amdgcn_sched_barrier(0);
;     sn = negm;
; #pragma unroll
;     for (int ds = 0; ds < 4; ++ds) sn = MFMA32(kf[ds], qf[ds], sn);
;     if (has_next) {
; #pragma unroll
;         for (int ds = 0; ds < 4; ++ds) kf[ds] = *(const LAS bf16x8*)(kb_next + ko[ds]);
;     }
;     __builtin_amdgcn_sched_barrier(0);
;     float mx = max3f(sc[0], sc[1], sc[2]), my = max3f(sc[3], sc[4], sc[5]);
;     mx = max3f(mx, sc[6], sc[7]); my = max3f(my, sc[8], sc[9]); mx = max3f(mx, sc[10], sc[11]); my = max3f(my, sc[12], sc[13]); mx = max3f(mx, sc[14], sc[15]);
;     mrun = max3f(mrun, mx, my);
;     float ps = 0.f;
; #pragma unroll
;     for (int i = 0; i < 16; ++i) { sc[i] = ex2(sc[i]); ps += sc[i]; }
;     lsum += ps;
;     u32x4 w0, w1;
;     w0.x = pk2(sc[0], sc[1]); w0.y = pk2(sc[2], sc[3]); w0.z = pk2(sc[4], sc[5]); w0.w = pk2(sc[6], sc[7]);
;     w1.x = pk2(sc[8], sc[9]); w1.y = pk2(sc[10], sc[11]); w1.z = pk2(sc[12], sc[13]); w1.w = pk2(sc[14], sc[15]);
;     const bf16x8 pf0 = __builtin_bit_cast(bf16x8, w0), pf1 = __builtin_bit_cast(bf16x8, w1);
; #pragma unroll
;     for (int cb = 0; cb < 4; ++cb) O[cb] = MFMA32(vf[cb], pf0, O[cb]);
; #pragma unroll
;     for (int cb = 0; cb < 4; ++cb) O[cb] = MFMA32(vf[4 + cb], pf1, O[cb]);
; }
; DI void diff_attn_phase(int wv, LAS unsigned char* lds, const bf16_t* QK, const bf16_t* VT, int rows, int nb, int S, bf16_t* OUT, const float* lq1, const float* lk1, const float* lq2, const float* lk2, float lam0, float lam1, int layer, const float* gsub) {
;     ...
;             DMA_KH(a + 2, 1); DMA_KH(a + 3, 0); DMA_KH(a + 3, 1); DMA_KH(a + 4, 0); DMA_V(a + 2); DMA_V(a + 3);
;             bf16x8 kf[4];
; #pragma unroll
;             for (int ds = 0; ds < 4; ++ds) kf[ds] = *(const LAS bf16x8*)(KS(0) + 8192 + ko[ds]);
;             attn_step32(sa, sb, O, negm, lsum, mrun, qf, kf, KS(1), true, VS(0), ko, vo[0], vo[1]);
.LBB0_290:
	s_add_i32 s43, s42, -2
	s_min_u32 s40, s43, s34
	s_cmp_lg_u64 s[14:15], 0
	s_cbranch_scc1 .Ldma_skip_a
	s_mov_b32 s47, m0
	s_cmp_eq_u32 s26, 64
	s_cselect_b32 s46, 20, 21
	s_lshl_b32 s46, 1, s46
	s_add_i32 s44, s42, -4
	s_min_u32 s44, s44, s34
	s_mov_b32 s45, s41
	s_lshl_b64 s[44:45], s[44:45], 18
	s_add_u32 s44, s79, s44
	s_addc_u32 s45, s80, s45
	s_add_u32 s44, s44, 0x400
	s_addc_u32 s45, s45, 0
	s_add_u32 s20, s44, 0x10000
	s_addc_u32 s21, s45, 0
	s_mov_b32 m0, s61
	s_nop 0
	global_load_lds_dwordx4 v245, s[44:45]
	s_add_i32 m0, s61, 0x1000
	s_nop 0
	global_load_lds_dwordx4 v245, s[20:21]
	s_add_i32 s44, s42, -3
	s_min_u32 s44, s44, s34
	s_mov_b32 s45, s41
	s_lshl_b64 s[44:45], s[44:45], 18
	s_add_u32 s44, s79, s44
	s_addc_u32 s45, s80, s45
	s_add_u32 s44, s44, 0x400
	s_addc_u32 s45, s45, 0
	s_add_u32 s20, s44, 0x10000
	s_addc_u32 s21, s45, 0
	s_mov_b32 m0, s62
	s_nop 0
	global_load_lds_dwordx4 v243, s[44:45]
	s_add_i32 m0, s62, 0x1000
	s_nop 0
	global_load_lds_dwordx4 v243, s[20:21]
	s_mov_b32 m0, s63
	s_nop 0
	global_load_lds_dwordx4 v245, s[44:45]
	s_add_i32 m0, s63, 0x1000
	s_nop 0
	global_load_lds_dwordx4 v245, s[20:21]
	s_lshl_b64 s[44:45], s[40:41], 18
	s_add_u32 s44, s79, s44
	s_addc_u32 s45, s80, s45
	s_add_u32 s44, s44, 0x400
	s_addc_u32 s45, s45, 0
	s_add_u32 s20, s44, 0x10000
	s_addc_u32 s21, s45, 0
	s_mov_b32 m0, s35
	s_nop 0
	global_load_lds_dwordx4 v243, s[44:45]
	s_add_i32 m0, s35, 0x1000
	s_nop 0
	global_load_lds_dwordx4 v243, s[20:21]
	s_add_i32 s44, s42, -4
	s_min_u32 s44, s44, s34
	s_mov_b32 s45, s41
	s_lshl_b64 s[44:45], s[44:45], 7
	s_add_u32 s44, s18, s44
	s_addc_u32 s45, s19, s45
	s_add_u32 s20, s44, s46
	s_addc_u32 s21, s45, 0
	s_mov_b32 m0, s64
	s_nop 0
	global_load_lds_dwordx4 v244, s[44:45]
	s_add_i32 m0, s64, 0x1000
	s_nop 0
	global_load_lds_dwordx4 v244, s[20:21]
	s_mov_b32 m0, s68
	s_nop 0
	global_load_lds_dwordx4 v246, s[44:45]
	s_add_i32 m0, s68, 0x1000
	s_nop 0
	global_load_lds_dwordx4 v246, s[20:21]
	s_add_i32 s44, s42, -3
	s_min_u32 s44, s44, s34
	s_mov_b32 s45, s41
	s_lshl_b64 s[44:45], s[44:45], 7
	s_add_u32 s44, s18, s44
	s_addc_u32 s45, s19, s45
	s_add_u32 s20, s44, s46
	s_addc_u32 s21, s45, 0
	s_mov_b32 m0, s65
	s_nop 0
	global_load_lds_dwordx4 v244, s[44:45]
	s_add_i32 m0, s65, 0x1000
	s_nop 0
	global_load_lds_dwordx4 v244, s[20:21]
	s_mov_b32 m0, s69
	s_nop 0
	global_load_lds_dwordx4 v246, s[44:45]
	s_add_i32 m0, s69, 0x1000
	s_nop 0
	global_load_lds_dwordx4 v246, s[20:21]
	s_mov_b32 m0, s47
.Ldma_skip_a:
	s_setprio 3
	s_add_i32 s33, 0, 0x10000
	v_add_u32_e32 v96, s33, v250
	ds_read_b128 v[112:115], v251 offset:8192
	ds_read_b128 v[116:119], v252 offset:8192
	ds_read_b128 v[120:123], v198 offset:8192
	ds_read_b128 v[124:127], v199 offset:8192
	v_add_u32_e32 v97, s33, v249
	ds_read_b128 v[144:147], v96
	ds_read_b128 v[148:151], v96 offset:4096
	ds_read_b128 v[152:155], v97
	ds_read_b128 v[156:159], v97 offset:4096
	ds_read_b128 v[160:163], v96 offset:8192
	ds_read_b128 v[164:167], v96 offset:12288
	ds_read_b128 v[168:171], v97 offset:8192
	ds_read_b128 v[194:197], v97 offset:12288
	s_waitcnt lgkmcnt(11)
	v_mfma_f32_32x32x16_bf16 v[96:111], v[112:115], v[128:131], v[64:79]
	ds_read_b128 v[220:223], v251 offset:16384
	ds_read_b128 v[224:227], v252 offset:16384
	ds_read_b128 v[228:231], v198 offset:16384
	ds_read_b128 v[232:235], v199 offset:16384
	s_waitcnt lgkmcnt(14)
	v_mfma_f32_32x32x16_bf16 v[96:111], v[116:119], v[132:135], v[96:111]
	s_waitcnt lgkmcnt(13)
	v_mfma_f32_32x32x16_bf16 v[96:111], v[120:123], v[136:139], v[96:111]
	s_waitcnt lgkmcnt(12)
	v_mfma_f32_32x32x16_bf16 v[96:111], v[124:127], v[140:143], v[96:111]
	v_exp_f32_e32 v116, v80
	v_exp_f32_e32 v180, v81
	v_exp_f32_e32 v184, v82
	v_exp_f32_e32 v182, v83
	v_exp_f32_e32 v188, v84
	v_exp_f32_e32 v186, v85
	v_exp_f32_e32 v202, v86
	v_exp_f32_e32 v190, v87
	v_cvt_pk_bf16_f32 v112, v116, v180
	v_cvt_pk_bf16_f32 v113, v184, v182
	v_cvt_pk_bf16_f32 v114, v188, v186
	v_cvt_pk_bf16_f32 v115, v202, v190
	v_exp_f32_e32 v206, v88
	v_exp_f32_e32 v204, v89
	s_waitcnt lgkmcnt(7)
	v_mfma_f32_32x32x16_bf16 v[16:31], v[160:163], v[112:115], v[16:31]
	v_exp_f32_e32 v210, v90
	v_exp_f32_e32 v208, v91
	v_exp_f32_e32 v212, v92
	v_exp_f32_e32 v214, v93
	v_exp_f32_e32 v218, v94
	v_exp_f32_e32 v216, v95
	v_max3_f32 v80, v80, v81, v82
	v_mfma_f32_32x32x16_bf16 v[48:63], v[144:147], v[112:115], v[48:63]
	v_max3_f32 v80, v80, v86, v87
	v_max3_f32 v81, v83, v84, v85
	v_cvt_pk_bf16_f32 v144, v206, v204
	v_max3_f32 v80, v80, v90, v91
	v_max3_f32 v81, v81, v88, v89
	v_cvt_pk_bf16_f32 v145, v210, v208
	v_max3_f32 v80, v80, v94, v95
	v_mfma_f32_32x32x16_bf16 v[32:47], v[148:151], v[112:115], v[32:47]
	v_cvt_pk_bf16_f32 v146, v212, v214
	v_cvt_pk_bf16_f32 v147, v218, v216
	v_max3_f32 v81, v81, v92, v93
	v_mov_b32_e32 v82, 0xf149f2ca
	v_max3_f32 v177, v82, v80, v81
	v_add_u32_e32 v80, s33, v248
	v_add_f32_e32 v192, 0, v116
	s_waitcnt lgkmcnt(6)
	v_mfma_f32_32x32x16_bf16 v[0:15], v[164:167], v[112:115], v[0:15]
	v_add_u32_e32 v81, s33, v247
	s_waitcnt lgkmcnt(5)
	v_mfma_f32_32x32x16_bf16 v[16:31], v[168:171], v[144:147], v[16:31]
	ds_read_b128 v[172:175], v80
	ds_read_b128 v[168:171], v80 offset:4096
	ds_read_b128 v[124:127], v81
	ds_read_b128 v[120:123], v81 offset:4096
	ds_read_b128 v[164:167], v80 offset:8192
	ds_read_b128 v[160:163], v80 offset:12288
	ds_read_b128 v[112:115], v81 offset:8192
	ds_read_b128 v[116:119], v81 offset:12288
	v_mfma_f32_32x32x16_bf16 v[48:63], v[152:155], v[144:147], v[48:63]
	v_mfma_f32_32x32x16_bf16 v[32:47], v[156:159], v[144:147], v[32:47]
	s_waitcnt lgkmcnt(12)
	v_mfma_f32_32x32x16_bf16 v[0:15], v[194:197], v[144:147], v[0:15]
	s_setprio 2
	s_waitcnt lgkmcnt(11)
; #define LAS __attribute__((address_space(3)))
; DI unsigned pk2(float lo, float hi) { f32x2 v = {lo, hi}; bf16x2_t b = __builtin_convertvector(v, bf16x2_t); return __builtin_bit_cast(unsigned, b); }
; DI float max3f(float a, float b, float c) { float r; asm("v_max3_f32 %0, %1, %2, %3" : "=v"(r) : "v"(a), "v"(b), "v"(c)); return r; }
; DI float ex2(float x) { return __builtin_amdgcn_exp2f(x); }
; #define MFMA32(a, b, c) __builtin_amdgcn_mfma_f32_32x32x16_bf16((a), (b), (c), 0, 0, 0)
; DI void attn_step32(f32x16& sc, f32x16& sn, f32x16 (&O)[4], const f32x16& negm, float& lsum, float& mrun, const bf16x8 (&qf)[4],
;                     bf16x8 (&kf)[4], const LAS unsigned char* kb_next, bool has_next, const LAS unsigned char* vb, const int (&ko)[4], int vo0, int vo1) {
;     bf16x8 vf[8];
; #pragma unroll
;     for (int cb = 0; cb < 4; ++cb) { vf[cb] = *(const LAS bf16x8*)(vb + vo0 + cb * 4096); vf[4 + cb] = *(const LAS bf16x8*)(vb + vo1 + cb * 4096); }
;     __builtin_amdgcn_sched_barrier(0);
;     sn = negm;
; #pragma unroll
;     for (int ds = 0; ds < 4; ++ds) sn = MFMA32(kf[ds], qf[ds], sn);
;     if (has_next) {
; #pragma unroll
;         for (int ds = 0; ds < 4; ++ds) kf[ds] = *(const LAS bf16x8*)(kb_next + ko[ds]);
;     }
;     __builtin_amdgcn_sched_barrier(0);
;     float mx = max3f(sc[0], sc[1], sc[2]), my = max3f(sc[3], sc[4], sc[5]);
;     mx = max3f(mx, sc[6], sc[7]); my = max3f(my, sc[8], sc[9]); mx = max3f(mx, sc[10], sc[11]); my = max3f(my, sc[12], sc[13]); mx = max3f(mx, sc[14], sc[15]);
;     mrun = max3f(mrun, mx, my);
;     float ps = 0.f;
; #pragma unroll
;     for (int i = 0; i < 16; ++i) { sc[i] = ex2(sc[i]); ps += sc[i]; }
;     lsum += ps;
;     u32x4 w0, w1;
;     w0.x = pk2(sc[0], sc[1]); w0.y = pk2(sc[2], sc[3]); w0.z = pk2(sc[4], sc[5]); w0.w = pk2(sc[6], sc[7]);
;     w1.x = pk2(sc[8], sc[9]); w1.y = pk2(sc[10], sc[11]); w1.z = pk2(sc[12], sc[13]); w1.w = pk2(sc[14], sc[15]);
;     const bf16x8 pf0 = __builtin_bit_cast(bf16x8, w0), pf1 = __builtin_bit_cast(bf16x8, w1);
; #pragma unroll
;     for (int cb = 0; cb < 4; ++cb) O[cb] = MFMA32(vf[cb], pf0, O[cb]);
; #pragma unroll
;     for (int cb = 0; cb < 4; ++cb) O[cb] = MFMA32(vf[4 + cb], pf1, O[cb]);
; }
	v_mfma_f32_32x32x16_bf16 v[80:95], v[220:223], v[128:131], v[64:79]
	ds_read_b128 v[156:159], v251 offset:24576
	ds_read_b128 v[152:155], v252 offset:24576
	ds_read_b128 v[144:147], v198 offset:24576
	ds_read_b128 v[148:151], v199 offset:24576
	s_waitcnt lgkmcnt(14)
	v_mfma_f32_32x32x16_bf16 v[80:95], v[224:227], v[132:135], v[80:95]
	s_waitcnt lgkmcnt(13)
	v_mfma_f32_32x32x16_bf16 v[80:95], v[228:231], v[136:139], v[80:95]
	s_waitcnt lgkmcnt(12)
	v_mfma_f32_32x32x16_bf16 v[80:95], v[232:235], v[140:143], v[80:95]
	v_exp_f32_e32 v181, v96
	v_exp_f32_e32 v185, v97
	v_exp_f32_e32 v183, v98
	v_exp_f32_e32 v189, v99
	v_max3_f32 v178, v96, v97, v98
	v_pk_add_f32 v[96:97], v[180:181], v[192:193]
	v_exp_f32_e32 v187, v100
	v_pk_add_f32 v[96:97], v[184:185], v[96:97]
	v_exp_f32_e32 v203, v101
	v_pk_add_f32 v[96:97], v[182:183], v[96:97]
	v_exp_f32_e32 v191, v102
	v_pk_add_f32 v[96:97], v[188:189], v[96:97]
	v_exp_f32_e32 v207, v103
	v_exp_f32_e32 v205, v104
	v_pk_add_f32 v[96:97], v[186:187], v[96:97]
	v_exp_f32_e32 v211, v105
	v_pk_add_f32 v[96:97], v[202:203], v[96:97]
	v_exp_f32_e32 v209, v106
	v_pk_add_f32 v[96:97], v[190:191], v[96:97]
	v_exp_f32_e32 v213, v107
	v_pk_add_f32 v[96:97], v[206:207], v[96:97]
	v_exp_f32_e32 v215, v108
	v_pk_add_f32 v[96:97], v[204:205], v[96:97]
	v_max3_f32 v179, v99, v100, v101
	v_max3_f32 v178, v178, v102, v103
	v_exp_f32_e32 v219, v109
	v_pk_add_f32 v[96:97], v[210:211], v[96:97]
	v_max3_f32 v179, v179, v104, v105
	v_max3_f32 v178, v178, v106, v107
	v_exp_f32_e32 v217, v110
	v_pk_add_f32 v[96:97], v[208:209], v[96:97]
	v_max3_f32 v179, v179, v108, v109
	v_max3_f32 v178, v178, v110, v111
	v_cvt_pk_bf16_f32 v98, v187, v203
	v_max3_f32 v194, v177, v178, v179
	v_exp_f32_e32 v177, v111
	v_pk_add_f32 v[96:97], v[212:213], v[96:97]
	v_cvt_pk_bf16_f32 v99, v191, v207
	v_pk_add_f32 v[96:97], v[214:215], v[96:97]
	v_cvt_pk_bf16_f32 v100, v205, v211
	v_pk_add_f32 v[96:97], v[218:219], v[96:97]
	v_cvt_pk_bf16_f32 v101, v209, v213
	v_pk_add_f32 v[96:97], v[216:217], v[96:97]
	v_cvt_pk_bf16_f32 v102, v215, v219
	v_pk_add_f32 v[178:179], v[176:177], v[96:97]
	v_cvt_pk_bf16_f32 v96, v181, v185
	v_cvt_pk_bf16_f32 v97, v183, v189
	v_cvt_pk_bf16_f32 v103, v217, v177
	s_add_i32 s33, 0, 0x14000
	s_waitcnt lgkmcnt(7)
	v_mfma_f32_32x32x16_bf16 v[16:31], v[164:167], v[96:99], v[16:31]
	v_mfma_f32_32x32x16_bf16 v[48:63], v[172:175], v[96:99], v[48:63]
	v_mfma_f32_32x32x16_bf16 v[32:47], v[168:171], v[96:99], v[32:47]
	s_waitcnt lgkmcnt(6)
	v_mfma_f32_32x32x16_bf16 v[0:15], v[160:163], v[96:99], v[0:15]
	s_waitcnt lgkmcnt(5)
	v_mfma_f32_32x32x16_bf16 v[16:31], v[112:115], v[100:103], v[16:31]
	v_add_u32_e32 v112, s33, v250
	v_add_u32_e32 v113, s33, v249
	ds_read_b128 v[96:99], v112
	v_mfma_f32_32x32x16_bf16 v[48:63], v[124:127], v[100:103], v[48:63]
	v_mfma_f32_32x32x16_bf16 v[32:47], v[120:123], v[100:103], v[32:47]
	s_waitcnt lgkmcnt(5)
	v_mfma_f32_32x32x16_bf16 v[0:15], v[116:119], v[100:103], v[0:15]
	ds_read_b128 v[100:103], v113
	ds_read_b128 v[104:107], v112 offset:4096
	ds_read_b128 v[108:111], v113 offset:4096
	ds_read_b128 v[174:177], v112 offset:8192
	ds_read_b128 v[202:205], v113 offset:8192
	ds_read_b128 v[186:189], v112 offset:12288
	ds_read_b128 v[206:209], v113 offset:12288
	s_setprio 1
	s_waitcnt lgkmcnt(11)
	v_mfma_f32_32x32x16_bf16 v[112:127], v[156:159], v[128:131], v[64:79]
	ds_read_b128 v[210:213], v251 offset:32768
	ds_read_b128 v[214:217], v252 offset:32768
	ds_read_b128 v[218:221], v198 offset:32768
	ds_read_b128 v[222:225], v199 offset:32768
	s_waitcnt lgkmcnt(14)
	v_mfma_f32_32x32x16_bf16 v[112:127], v[152:155], v[132:135], v[112:127]
	s_waitcnt lgkmcnt(13)
	v_mfma_f32_32x32x16_bf16 v[112:127], v[144:147], v[136:139], v[112:127]
	s_waitcnt lgkmcnt(12)
	v_mfma_f32_32x32x16_bf16 v[112:127], v[148:151], v[140:143], v[112:127]
	v_exp_f32_e32 v148, v80
	v_exp_f32_e32 v160, v81
	v_exp_f32_e32 v164, v82
	v_exp_f32_e32 v162, v83
	v_exp_f32_e32 v168, v84
	v_exp_f32_e32 v166, v85
	v_exp_f32_e32 v172, v86
	v_exp_f32_e32 v170, v87
	v_cvt_pk_bf16_f32 v144, v148, v160
	v_cvt_pk_bf16_f32 v145, v164, v162
	v_cvt_pk_bf16_f32 v146, v168, v166
	v_cvt_pk_bf16_f32 v147, v172, v170
	v_max3_f32 v80, v80, v81, v82
	v_max3_f32 v81, v83, v84, v85
	v_exp_f32_e32 v182, v90
	v_max3_f32 v80, v80, v86, v87
	v_exp_f32_e32 v180, v91
	s_waitcnt lgkmcnt(11)
	v_mfma_f32_32x32x16_bf16 v[48:63], v[96:99], v[144:147], v[48:63]
	v_max3_f32 v80, v80, v90, v91
	v_exp_f32_e32 v184, v92
	v_exp_f32_e32 v190, v94
	v_max3_f32 v81, v81, v88, v89
	v_max3_f32 v80, v80, v94, v95
	v_add_u32_e32 v84, s33, v247
	v_max3_f32 v81, v81, v92, v93
	s_waitcnt lgkmcnt(9)
	v_mfma_f32_32x32x16_bf16 v[32:47], v[104:107], v[144:147], v[32:47]
	v_max3_f32 v161, v194, v80, v81
	v_add_u32_e32 v80, s33, v248
	v_add_f32_e32 v192, 0, v148
	v_cvt_pk_bf16_f32 v97, v182, v180
	s_waitcnt lgkmcnt(7)
	v_mfma_f32_32x32x16_bf16 v[16:31], v[174:177], v[144:147], v[16:31]
	v_exp_f32_e32 v176, v88
	v_exp_f32_e32 v174, v89
	s_nop 0
	v_cvt_pk_bf16_f32 v96, v176, v174
	s_waitcnt lgkmcnt(5)
	v_mfma_f32_32x32x16_bf16 v[0:15], v[186:189], v[144:147], v[0:15]
	v_exp_f32_e32 v186, v93
	v_exp_f32_e32 v188, v95
	ds_read_b128 v[156:159], v80
	ds_read_b128 v[152:155], v80 offset:4096
	ds_read_b128 v[92:95], v84
	ds_read_b128 v[88:91], v84 offset:4096
	ds_read_b128 v[148:151], v80 offset:8192
	ds_read_b128 v[144:147], v80 offset:12288
	ds_read_b128 v[80:83], v84 offset:8192
	ds_read_b128 v[84:87], v84 offset:12288
	v_cvt_pk_bf16_f32 v98, v184, v186
	v_cvt_pk_bf16_f32 v99, v190, v188
	s_nop 1
	v_mfma_f32_32x32x16_bf16 v[48:63], v[100:103], v[96:99], v[48:63]
	v_mfma_f32_32x32x16_bf16 v[32:47], v[108:111], v[96:99], v[32:47]
	v_mfma_f32_32x32x16_bf16 v[16:31], v[202:205], v[96:99], v[16:31]
	s_waitcnt lgkmcnt(12)
; #define LAS __attribute__((address_space(3)))
; DI float ex2(float x) { return __builtin_amdgcn_exp2f(x); }
; DI void attn_step32(f32x16& sc, f32x16& sn, f32x16 (&O)[4], const f32x16& negm, float& lsum, float& mrun, const bf16x8 (&qf)[4],
;                     bf16x8 (&kf)[4], const LAS unsigned char* kb_next, bool has_next, const LAS unsigned char* vb, const int (&ko)[4], int vo0, int vo1) {
;     bf16x8 vf[8];
; #pragma unroll
;     for (int cb = 0; cb < 4; ++cb) { vf[cb] = *(const LAS bf16x8*)(vb + vo0 + cb * 4096); vf[4 + cb] = *(const LAS bf16x8*)(vb + vo1 + cb * 4096); }
;     __builtin_amdgcn_sched_barrier(0);
;     sn = negm;
; #pragma unroll
;     for (int ds = 0; ds < 4; ++ds) sn = MFMA32(kf[ds], qf[ds], sn);
;     if (has_next) {
; #pragma unroll
;         for (int ds = 0; ds < 4; ++ds) kf[ds] = *(const LAS bf16x8*)(kb_next + ko[ds]);
;     }
;     __builtin_amdgcn_sched_barrier(0);
;     float mx = max3f(sc[0], sc[1], sc[2]), my = max3f(sc[3], sc[4], sc[5]);
;     mx = max3f(mx, sc[6], sc[7]); my = max3f(my, sc[8], sc[9]); mx = max3f(mx, sc[10], sc[11]); my = max3f(my, sc[12], sc[13]); mx = max3f(mx, sc[14], sc[15]);
;     mrun = max3f(mrun, mx, my);
;     float ps = 0.f;
; #pragma unroll
;     for (int i = 0; i < 16; ++i) { sc[i] = ex2(sc[i]); ps += sc[i]; }
;     lsum += ps;
;     u32x4 w0, w1;
;     w0.x = pk2(sc[0], sc[1]); w0.y = pk2(sc[2], sc[3]); w0.z = pk2(sc[4], sc[5]); w0.w = pk2(sc[6], sc[7]);
;     w1.x = pk2(sc[8], sc[9]); w1.y = pk2(sc[10], sc[11]); w1.z = pk2(sc[12], sc[13]); w1.w = pk2(sc[14], sc[15]);
;     const bf16x8 pf0 = __builtin_bit_cast(bf16x8, w0), pf1 = __builtin_bit_cast(bf16x8, w1);
; #pragma unroll
;     for (int cb = 0; cb < 4; ++cb) O[cb] = MFMA32(vf[cb], pf0, O[cb]);
; #pragma unroll
;     for (int cb = 0; cb < 4; ++cb) O[cb] = MFMA32(vf[4 + cb], pf1, O[cb]);
; }
; DI void attn_renorm(f32x16& spend, f32x16 (&O)[4], f32x16& negm, float& mref, float& lsum, float& mrun) {
;     constexpr float THR = 6.0f;
;     const float mx = swap_max(mrun);
;     if (__any(mx > THR)) {
;         const float dl = fmaxf(mx, 0.f), alpha = ex2(-dl);
;         mref += dl; lsum *= alpha;
; #pragma unroll
;         for (int cb = 0; cb < 4; ++cb) O[cb] = O[cb] * alpha;
; #pragma unroll
;         for (int i = 0; i < 16; ++i) { spend[i] -= dl; negm[i] = -mref; }
;     }
;     mrun = -1.0e30f;
; }
	v_mfma_f32_32x32x16_bf16 v[0:15], v[206:209], v[96:99], v[0:15]
	s_setprio 0
	s_waitcnt lgkmcnt(11)
	v_mfma_f32_32x32x16_bf16 v[96:111], v[210:213], v[128:131], v[64:79]
	s_waitcnt lgkmcnt(10)
	v_mfma_f32_32x32x16_bf16 v[96:111], v[214:217], v[132:135], v[96:111]
	s_waitcnt lgkmcnt(9)
	v_mfma_f32_32x32x16_bf16 v[96:111], v[218:221], v[136:139], v[96:111]
	s_waitcnt lgkmcnt(8)
	v_mfma_f32_32x32x16_bf16 v[96:111], v[222:225], v[140:143], v[96:111]
	v_max3_f32 v163, v112, v113, v114
	v_max3_f32 v165, v115, v116, v117
	v_exp_f32_e32 v169, v115
	v_max3_f32 v163, v163, v118, v119
	v_max3_f32 v165, v165, v120, v121
	v_exp_f32_e32 v167, v116
	v_max3_f32 v163, v163, v122, v123
	v_max3_f32 v165, v165, v124, v125
	v_exp_f32_e32 v173, v117
	v_max3_f32 v163, v163, v126, v127
	v_exp_f32_e32 v171, v118
	v_max3_f32 v194, v161, v163, v165
	v_exp_f32_e32 v161, v112
	v_exp_f32_e32 v165, v113
	v_exp_f32_e32 v163, v114
	v_exp_f32_e32 v177, v119
	v_pk_add_f32 v[112:113], v[160:161], v[192:193]
	v_exp_f32_e32 v175, v120
	v_pk_add_f32 v[112:113], v[164:165], v[112:113]
	v_exp_f32_e32 v183, v121
	v_pk_add_f32 v[112:113], v[162:163], v[112:113]
	v_exp_f32_e32 v181, v122
	v_pk_add_f32 v[112:113], v[168:169], v[112:113]
	v_exp_f32_e32 v185, v123
	v_pk_add_f32 v[112:113], v[166:167], v[112:113]
	v_exp_f32_e32 v187, v124
	v_pk_add_f32 v[112:113], v[172:173], v[112:113]
	v_exp_f32_e32 v191, v125
	v_pk_add_f32 v[112:113], v[170:171], v[112:113]
	v_exp_f32_e32 v189, v126
	v_pk_add_f32 v[112:113], v[176:177], v[112:113]
	v_exp_f32_e32 v119, v127
	v_pk_add_f32 v[112:113], v[174:175], v[112:113]
	v_pk_add_f32 v[114:115], v[178:179], v[178:179] op_sel:[0,1] op_sel_hi:[1,0]
	v_pk_add_f32 v[112:113], v[182:183], v[112:113]
	v_mov_b32_e32 v115, v119
	v_pk_add_f32 v[112:113], v[180:181], v[112:113]
	v_cvt_pk_bf16_f32 v116, v175, v183
	v_pk_add_f32 v[112:113], v[184:185], v[112:113]
	v_cvt_pk_bf16_f32 v117, v181, v185
	v_pk_add_f32 v[112:113], v[186:187], v[112:113]
	v_cvt_pk_bf16_f32 v118, v187, v191
	v_pk_add_f32 v[112:113], v[190:191], v[112:113]
	v_cvt_pk_bf16_f32 v119, v189, v119
	v_pk_add_f32 v[112:113], v[188:189], v[112:113]
	s_nop 0
	v_pk_add_f32 v[112:113], v[114:115], v[112:113]
	v_cvt_pk_bf16_f32 v114, v167, v173
	v_add_f32_e32 v202, v112, v113
	v_cvt_pk_bf16_f32 v112, v161, v165
	v_cvt_pk_bf16_f32 v113, v163, v169
	v_cvt_pk_bf16_f32 v115, v171, v177
	s_waitcnt lgkmcnt(7)
	s_nop 0
	v_mfma_f32_32x32x16_bf16 v[48:63], v[156:159], v[112:115], v[48:63]
	s_waitcnt lgkmcnt(6)
	v_mfma_f32_32x32x16_bf16 v[32:47], v[152:155], v[112:115], v[32:47]
	s_waitcnt lgkmcnt(3)
	v_mfma_f32_32x32x16_bf16 v[16:31], v[148:151], v[112:115], v[16:31]
	s_waitcnt lgkmcnt(2)
	v_mfma_f32_32x32x16_bf16 v[0:15], v[144:147], v[112:115], v[0:15]
	v_mfma_f32_32x32x16_bf16 v[48:63], v[92:95], v[116:119], v[48:63]
	v_mfma_f32_32x32x16_bf16 v[32:47], v[88:91], v[116:119], v[32:47]
	s_waitcnt lgkmcnt(1)
	v_mfma_f32_32x32x16_bf16 v[16:31], v[80:83], v[116:119], v[16:31]
	v_mov_b32_e32 v80, v194
	s_nop 1
	v_permlane32_swap_b32_e32 v194, v80
	v_max_f32_e32 v80, v80, v80
	v_max_f32_e32 v81, v194, v194
	v_max_f32_e32 v80, v81, v80
	v_cmp_lt_f32_e32 vcc, s95, v80
	s_waitcnt lgkmcnt(0)
	v_mfma_f32_32x32x16_bf16 v[0:15], v[84:87], v[116:119], v[0:15]
	s_cbranch_vccz .LBB0_292
	v_max_f32_e32 v64, v80, v80
	v_max_f32_e32 v65, 0, v64
	v_exp_f32_e64 v64, -v65
	v_add_f32_e32 v200, v200, v65
	v_xor_b32_e32 v80, 0x80000000, v200
	v_sub_f32_e32 v111, v111, v65
	v_mul_f32_e32 v202, v202, v64
	v_pk_mul_f32 v[62:63], v[62:63], v[64:65] op_sel_hi:[1,0]
	v_pk_mul_f32 v[60:61], v[60:61], v[64:65] op_sel_hi:[1,0]
	v_pk_mul_f32 v[58:59], v[58:59], v[64:65] op_sel_hi:[1,0]
	v_pk_mul_f32 v[56:57], v[56:57], v[64:65] op_sel_hi:[1,0]
	v_pk_mul_f32 v[54:55], v[54:55], v[64:65] op_sel_hi:[1,0]
	v_pk_mul_f32 v[52:53], v[52:53], v[64:65] op_sel_hi:[1,0]
	v_pk_mul_f32 v[50:51], v[50:51], v[64:65] op_sel_hi:[1,0]
	v_pk_mul_f32 v[48:49], v[48:49], v[64:65] op_sel_hi:[1,0]
	v_pk_mul_f32 v[46:47], v[46:47], v[64:65] op_sel_hi:[1,0]
	v_pk_mul_f32 v[44:45], v[44:45], v[64:65] op_sel_hi:[1,0]
	v_pk_mul_f32 v[42:43], v[42:43], v[64:65] op_sel_hi:[1,0]
	v_pk_mul_f32 v[40:41], v[40:41], v[64:65] op_sel_hi:[1,0]
	v_pk_mul_f32 v[38:39], v[38:39], v[64:65] op_sel_hi:[1,0]
	v_pk_mul_f32 v[36:37], v[36:37], v[64:65] op_sel_hi:[1,0]
	v_pk_mul_f32 v[34:35], v[34:35], v[64:65] op_sel_hi:[1,0]
	v_pk_mul_f32 v[32:33], v[32:33], v[64:65] op_sel_hi:[1,0]
	v_pk_mul_f32 v[30:31], v[30:31], v[64:65] op_sel_hi:[1,0]
	v_pk_mul_f32 v[28:29], v[28:29], v[64:65] op_sel_hi:[1,0]
	v_pk_mul_f32 v[26:27], v[26:27], v[64:65] op_sel_hi:[1,0]
	v_pk_mul_f32 v[24:25], v[24:25], v[64:65] op_sel_hi:[1,0]
	v_pk_mul_f32 v[22:23], v[22:23], v[64:65] op_sel_hi:[1,0]
	v_pk_mul_f32 v[20:21], v[20:21], v[64:65] op_sel_hi:[1,0]
	v_pk_mul_f32 v[18:19], v[18:19], v[64:65] op_sel_hi:[1,0]
	v_pk_mul_f32 v[16:17], v[16:17], v[64:65] op_sel_hi:[1,0]
	v_pk_mul_f32 v[14:15], v[14:15], v[64:65] op_sel_hi:[1,0]
	v_pk_mul_f32 v[12:13], v[12:13], v[64:65] op_sel_hi:[1,0]
	v_pk_mul_f32 v[10:11], v[10:11], v[64:65] op_sel_hi:[1,0]
	v_pk_mul_f32 v[8:9], v[8:9], v[64:65] op_sel_hi:[1,0]
	v_pk_mul_f32 v[6:7], v[6:7], v[64:65] op_sel_hi:[1,0]
	v_pk_mul_f32 v[4:5], v[4:5], v[64:65] op_sel_hi:[1,0]
	v_pk_mul_f32 v[2:3], v[2:3], v[64:65] op_sel_hi:[1,0]
	v_pk_mul_f32 v[0:1], v[0:1], v[64:65] op_sel_hi:[1,0]
	v_sub_f32_e32 v110, v110, v65
	v_sub_f32_e32 v109, v109, v65
	v_sub_f32_e32 v108, v108, v65
	v_sub_f32_e32 v107, v107, v65
	v_sub_f32_e32 v106, v106, v65
	v_sub_f32_e32 v105, v105, v65
	v_sub_f32_e32 v104, v104, v65
	v_sub_f32_e32 v103, v103, v65
	v_sub_f32_e32 v102, v102, v65
	v_sub_f32_e32 v101, v101, v65
	v_sub_f32_e32 v100, v100, v65
	v_sub_f32_e32 v99, v99, v65
	v_sub_f32_e32 v98, v98, v65
	v_sub_f32_e32 v97, v97, v65
	v_sub_f32_e32 v96, v96, v65
	v_mov_b32_e32 v81, v80
	v_mov_b32_e32 v82, v80
	v_mov_b32_e32 v83, v80
	v_mov_b32_e32 v84, v80
	v_mov_b32_e32 v85, v80
	v_mov_b32_e32 v86, v80
	v_mov_b32_e32 v87, v80
	v_mov_b32_e32 v88, v80
	v_mov_b32_e32 v89, v80
	v_mov_b32_e32 v90, v80
	v_mov_b32_e32 v91, v80
	v_mov_b32_e32 v92, v80
	v_mov_b32_e32 v93, v80
	v_mov_b32_e32 v94, v80
	v_mov_b32_e32 v95, v80
	v_mov_b32_e32 v64, v80
	v_mov_b32_e32 v65, v80
	v_mov_b32_e32 v66, v80
	v_mov_b32_e32 v67, v80
	v_mov_b32_e32 v68, v80
	v_mov_b32_e32 v69, v80
	v_mov_b32_e32 v70, v80
	v_mov_b32_e32 v71, v80
	v_mov_b32_e32 v72, v80
	v_mov_b32_e32 v73, v80
	v_mov_b32_e32 v74, v80
	v_mov_b32_e32 v75, v80
	v_mov_b32_e32 v76, v80
	v_mov_b32_e32 v77, v80
	v_mov_b32_e32 v78, v80
	v_mov_b32_e32 v79, v80
	s_branch .LBB0_293

; DI void attn_step32(f32x16& sc, f32x16& sn, f32x16 (&O)[4], const f32x16& negm, float& lsum, float& mrun, const bf16x8 (&qf)[4],
;                     bf16x8 (&kf)[4], const LAS unsigned char* kb_next, bool has_next, const LAS unsigned char* vb, const int (&ko)[4], int vo0, int vo1) {
;     bf16x8 vf[8];
; #pragma unroll
;     for (int cb = 0; cb < 4; ++cb) { vf[cb] = *(const LAS bf16x8*)(vb + vo0 + cb * 4096); vf[4 + cb] = *(const LAS bf16x8*)(vb + vo1 + cb * 4096); }
;     __builtin_amdgcn_sched_barrier(0);
;     sn = negm;
; #pragma unroll
;     for (int ds = 0; ds < 4; ++ds) sn = MFMA32(kf[ds], qf[ds], sn);
;     if (has_next) {
; #pragma unroll
;         for (int ds = 0; ds < 4; ++ds) kf[ds] = *(const LAS bf16x8*)(kb_next + ko[ds]);
;     }
;     __builtin_amdgcn_sched_barrier(0);
;     float mx = max3f(sc[0], sc[1], sc[2]), my = max3f(sc[3], sc[4], sc[5]);
;     mx = max3f(mx, sc[6], sc[7]); my = max3f(my, sc[8], sc[9]); mx = max3f(mx, sc[10], sc[11]); my = max3f(my, sc[12], sc[13]); mx = max3f(mx, sc[14], sc[15]);
;     mrun = max3f(mrun, mx, my);
;     float ps = 0.f;
; #pragma unroll
;     for (int i = 0; i < 16; ++i) { sc[i] = ex2(sc[i]); ps += sc[i]; }
;     lsum += ps;
;     u32x4 w0, w1;
;     w0.x = pk2(sc[0], sc[1]); w0.y = pk2(sc[2], sc[3]); w0.z = pk2(sc[4], sc[5]); w0.w = pk2(sc[6], sc[7]);
;     w1.x = pk2(sc[8], sc[9]); w1.y = pk2(sc[10], sc[11]); w1.z = pk2(sc[12], sc[13]); w1.w = pk2(sc[14], sc[15]);
;     const bf16x8 pf0 = __builtin_bit_cast(bf16x8, w0), pf1 = __builtin_bit_cast(bf16x8, w1);
; #pragma unroll
;     for (int cb = 0; cb < 4; ++cb) O[cb] = MFMA32(vf[cb], pf0, O[cb]);
; #pragma unroll
;     for (int cb = 0; cb < 4; ++cb) O[cb] = MFMA32(vf[4 + cb], pf1, O[cb]);
; DI void diff_attn_phase(int wv, LAS unsigned char* lds, const bf16_t* QK, const bf16_t* VT, int rows, int nb, int S, bf16_t* OUT, const float* lq1, const float* lk1, const float* lq2, const float* lk2, float lam0, float lam1, int layer, const float* gsub) {
;     ...
;             asm volatile("s_waitcnt vmcnt(0)" ::: "memory"); __syncthreads();
;             DMA_KH(a + 4, 1); DMA_KH(a + 5, 0); DMA_KH(a + 5, 1); DMA_KH(a + 6, 0); DMA_V(a + 4); DMA_V(a + 5);
; #pragma unroll
;             for (int ds = 0; ds < 4; ++ds) kf[ds] = *(const LAS bf16x8*)(KS(2) + 8192 + ko[ds]);
;             attn_step32(sa, sb, O, negm, lsum, mrun, qf, kf, KS(3), true, VS(2), ko, vo[0], vo[1]);
.LBB0_293:
	s_waitcnt vmcnt(0)
	s_barrier
	s_cmp_lg_u64 s[14:15], 0
	s_cbranch_scc1 .Ldma_skip_b
	s_mov_b32 s47, m0
	s_cmp_eq_u32 s26, 64
	s_cselect_b32 s46, 20, 21
	s_lshl_b32 s46, 1, s46
	s_lshl_b64 s[44:45], s[40:41], 18
	s_add_u32 s44, s79, s44
	s_addc_u32 s45, s80, s45
	s_add_u32 s44, s44, 0x400
	s_addc_u32 s45, s45, 0
	s_add_u32 s20, s44, 0x10000
	s_addc_u32 s21, s45, 0
	s_mov_b32 m0, s36
	s_nop 0
	global_load_lds_dwordx4 v245, s[44:45]
	s_add_i32 m0, s36, 0x1000
	s_nop 0
	global_load_lds_dwordx4 v245, s[20:21]
	s_add_i32 s44, s42, -1
	s_min_u32 s44, s44, s34
	s_mov_b32 s45, s41
	s_lshl_b64 s[44:45], s[44:45], 18
	s_add_u32 s44, s79, s44
	s_addc_u32 s45, s80, s45
	s_add_u32 s44, s44, 0x400
	s_addc_u32 s45, s45, 0
	s_add_u32 s20, s44, 0x10000
	s_addc_u32 s21, s45, 0
	s_mov_b32 m0, s38
	s_nop 0
	global_load_lds_dwordx4 v243, s[44:45]
	s_add_i32 m0, s38, 0x1000
	s_nop 0
	global_load_lds_dwordx4 v243, s[20:21]
	s_mov_b32 m0, s39
	s_nop 0
	global_load_lds_dwordx4 v245, s[44:45]
	s_add_i32 m0, s39, 0x1000
	s_nop 0
	global_load_lds_dwordx4 v245, s[20:21]
	s_min_u32 s44, s42, s34
	s_mov_b32 s45, s41
	s_lshl_b64 s[44:45], s[44:45], 18
	s_add_u32 s44, s79, s44
	s_addc_u32 s45, s80, s45
	s_add_u32 s44, s44, 0x400
	s_addc_u32 s45, s45, 0
	s_add_u32 s20, s44, 0x10000
	s_addc_u32 s21, s45, 0
	s_mov_b32 m0, s59
	s_nop 0
	global_load_lds_dwordx4 v243, s[44:45]
	s_add_i32 m0, s59, 0x1000
	s_nop 0
	global_load_lds_dwordx4 v243, s[20:21]
	s_lshl_b64 s[44:45], s[40:41], 7
	s_add_u32 s44, s18, s44
	s_addc_u32 s45, s19, s45
	s_add_u32 s20, s44, s46
	s_addc_u32 s21, s45, 0
	s_mov_b32 m0, s37
	s_nop 0
	global_load_lds_dwordx4 v244, s[44:45]
	s_add_i32 m0, s37, 0x1000
	s_nop 0
	global_load_lds_dwordx4 v244, s[20:21]
	s_mov_b32 m0, s66
	s_nop 0
	global_load_lds_dwordx4 v246, s[44:45]
	s_add_i32 m0, s66, 0x1000
	s_nop 0
	global_load_lds_dwordx4 v246, s[20:21]
	s_add_i32 s44, s42, -1
	s_min_u32 s44, s44, s34
	s_mov_b32 s45, s41
	s_lshl_b64 s[44:45], s[44:45], 7
	s_add_u32 s44, s18, s44
	s_addc_u32 s45, s19, s45
	s_add_u32 s20, s44, s46
	s_addc_u32 s21, s45, 0
	s_mov_b32 m0, s60
	s_nop 0
	global_load_lds_dwordx4 v244, s[44:45]
	s_add_i32 m0, s60, 0x1000
	s_nop 0
	global_load_lds_dwordx4 v244, s[20:21]
	s_mov_b32 m0, s67
	s_nop 0
	global_load_lds_dwordx4 v246, s[44:45]
	s_add_i32 m0, s67, 0x1000
	s_nop 0
	global_load_lds_dwordx4 v246, s[20:21]
	s_mov_b32 m0, s47
.Ldma_skip_b:
	s_setprio 3
	s_add_i32 s20, 0, 0x18000
	v_add_u32_e32 v112, s20, v250
	ds_read_b128 v[144:147], v251 offset:40960
	ds_read_b128 v[148:151], v252 offset:40960
	ds_read_b128 v[152:155], v198 offset:40960
	ds_read_b128 v[156:159], v199 offset:40960
	v_add_u32_e32 v113, s20, v249
	ds_read_b128 v[160:163], v112
	ds_read_b128 v[164:167], v112 offset:4096
	ds_read_b128 v[168:171], v113
	ds_read_b128 v[172:175], v113 offset:4096
	ds_read_b128 v[176:179], v112 offset:8192
	ds_read_b128 v[180:183], v112 offset:12288
	ds_read_b128 v[184:187], v113 offset:8192
	ds_read_b128 v[194:197], v113 offset:12288
	s_waitcnt lgkmcnt(11)
	v_mfma_f32_32x32x16_bf16 v[112:127], v[144:147], v[128:131], v[80:95]
	s_waitcnt lgkmcnt(10)
	v_mfma_f32_32x32x16_bf16 v[112:127], v[148:151], v[132:135], v[112:127]
	s_waitcnt lgkmcnt(9)
	v_mfma_f32_32x32x16_bf16 v[112:127], v[152:155], v[136:139], v[112:127]
	s_waitcnt lgkmcnt(8)
	v_mfma_f32_32x32x16_bf16 v[112:127], v[156:159], v[140:143], v[112:127]
	ds_read_b128 v[144:147], v251 offset:49152
	ds_read_b128 v[148:151], v252 offset:49152
	ds_read_b128 v[152:155], v198 offset:49152
	ds_read_b128 v[156:159], v199 offset:49152
	v_exp_f32_e32 v192, v96
	v_exp_f32_e32 v206, v97
	v_exp_f32_e32 v210, v98
	v_exp_f32_e32 v208, v99
	v_exp_f32_e32 v214, v100
	v_exp_f32_e32 v212, v101
	v_exp_f32_e32 v218, v102
	v_exp_f32_e32 v216, v103
	v_cvt_pk_bf16_f32 v188, v192, v206
	v_cvt_pk_bf16_f32 v189, v210, v208
	v_cvt_pk_bf16_f32 v190, v214, v212
	v_cvt_pk_bf16_f32 v191, v218, v216
	v_exp_f32_e32 v222, v104
	v_exp_f32_e32 v220, v105
	s_waitcnt lgkmcnt(11)
	v_mfma_f32_32x32x16_bf16 v[48:63], v[160:163], v[188:191], v[48:63]
	v_exp_f32_e32 v226, v106
	v_exp_f32_e32 v224, v107
	v_exp_f32_e32 v228, v108
	v_exp_f32_e32 v230, v109
	v_exp_f32_e32 v234, v110
	v_exp_f32_e32 v232, v111
	v_max3_f32 v96, v96, v97, v98
	s_waitcnt lgkmcnt(10)
	v_mfma_f32_32x32x16_bf16 v[32:47], v[164:167], v[188:191], v[32:47]
	v_max3_f32 v96, v96, v102, v103
	v_max3_f32 v97, v99, v100, v101
	v_cvt_pk_bf16_f32 v236, v222, v220
	v_max3_f32 v96, v96, v106, v107
	v_max3_f32 v97, v97, v104, v105
	v_cvt_pk_bf16_f32 v237, v226, v224
	v_max3_f32 v96, v96, v110, v111
	s_waitcnt lgkmcnt(7)
	v_mfma_f32_32x32x16_bf16 v[16:31], v[176:179], v[188:191], v[16:31]
	v_cvt_pk_bf16_f32 v238, v228, v230
	v_cvt_pk_bf16_f32 v239, v234, v232
	v_max3_f32 v97, v97, v108, v109
	v_mov_b32_e32 v98, 0xf149f2ca
	v_max3_f32 v201, v98, v96, v97
	v_add_u32_e32 v96, s20, v248
	v_add_u32_e32 v97, s20, v247
	s_waitcnt lgkmcnt(6)
	v_mfma_f32_32x32x16_bf16 v[0:15], v[180:183], v[188:191], v[0:15]
	v_add_f32_e32 v192, 0, v192
	v_mfma_f32_32x32x16_bf16 v[48:63], v[168:171], v[236:239], v[48:63]
	v_mfma_f32_32x32x16_bf16 v[32:47], v[172:175], v[236:239], v[32:47]
	s_waitcnt lgkmcnt(5)
	v_mfma_f32_32x32x16_bf16 v[16:31], v[184:187], v[236:239], v[16:31]
	ds_read_b128 v[188:191], v96
	ds_read_b128 v[184:187], v96 offset:4096
	ds_read_b128 v[172:175], v97
	ds_read_b128 v[168:171], v97 offset:4096
	ds_read_b128 v[180:183], v96 offset:8192
	ds_read_b128 v[176:179], v96 offset:12288
	ds_read_b128 v[160:163], v97 offset:8192
	ds_read_b128 v[164:167], v97 offset:12288
	s_waitcnt lgkmcnt(12)
	v_mfma_f32_32x32x16_bf16 v[0:15], v[194:197], v[236:239], v[0:15]
	s_setprio 2
	s_waitcnt lgkmcnt(11)
; #define LAS __attribute__((address_space(3)))
; DI unsigned pk2(float lo, float hi) { f32x2 v = {lo, hi}; bf16x2_t b = __builtin_convertvector(v, bf16x2_t); return __builtin_bit_cast(unsigned, b); }
; DI float max3f(float a, float b, float c) { float r; asm("v_max3_f32 %0, %1, %2, %3" : "=v"(r) : "v"(a), "v"(b), "v"(c)); return r; }
; DI float ex2(float x) { return __builtin_amdgcn_exp2f(x); }
; #define MFMA32(a, b, c) __builtin_amdgcn_mfma_f32_32x32x16_bf16((a), (b), (c), 0, 0, 0)
; DI void attn_step32(f32x16& sc, f32x16& sn, f32x16 (&O)[4], const f32x16& negm, float& lsum, float& mrun, const bf16x8 (&qf)[4],
;                     bf16x8 (&kf)[4], const LAS unsigned char* kb_next, bool has_next, const LAS unsigned char* vb, const int (&ko)[4], int vo0, int vo1) {
;     bf16x8 vf[8];
; #pragma unroll
;     for (int cb = 0; cb < 4; ++cb) { vf[cb] = *(const LAS bf16x8*)(vb + vo0 + cb * 4096); vf[4 + cb] = *(const LAS bf16x8*)(vb + vo1 + cb * 4096); }
;     __builtin_amdgcn_sched_barrier(0);
;     sn = negm;
; #pragma unroll
;     for (int ds = 0; ds < 4; ++ds) sn = MFMA32(kf[ds], qf[ds], sn);
;     if (has_next) {
; #pragma unroll
;         for (int ds = 0; ds < 4; ++ds) kf[ds] = *(const LAS bf16x8*)(kb_next + ko[ds]);
;     }
;     __builtin_amdgcn_sched_barrier(0);
;     float mx = max3f(sc[0], sc[1], sc[2]), my = max3f(sc[3], sc[4], sc[5]);
;     mx = max3f(mx, sc[6], sc[7]); my = max3f(my, sc[8], sc[9]); mx = max3f(mx, sc[10], sc[11]); my = max3f(my, sc[12], sc[13]); mx = max3f(mx, sc[14], sc[15]);
;     mrun = max3f(mrun, mx, my);
;     float ps = 0.f;
; #pragma unroll
;     for (int i = 0; i < 16; ++i) { sc[i] = ex2(sc[i]); ps += sc[i]; }
;     lsum += ps;
;     u32x4 w0, w1;
;     w0.x = pk2(sc[0], sc[1]); w0.y = pk2(sc[2], sc[3]); w0.z = pk2(sc[4], sc[5]); w0.w = pk2(sc[6], sc[7]);
;     w1.x = pk2(sc[8], sc[9]); w1.y = pk2(sc[10], sc[11]); w1.z = pk2(sc[12], sc[13]); w1.w = pk2(sc[14], sc[15]);
;     const bf16x8 pf0 = __builtin_bit_cast(bf16x8, w0), pf1 = __builtin_bit_cast(bf16x8, w1);
; #pragma unroll
;     for (int cb = 0; cb < 4; ++cb) O[cb] = MFMA32(vf[cb], pf0, O[cb]);
; #pragma unroll
;     for (int cb = 0; cb < 4; ++cb) O[cb] = MFMA32(vf[4 + cb], pf1, O[cb]);
; }
	v_mfma_f32_32x32x16_bf16 v[96:111], v[144:147], v[128:131], v[80:95]
	s_waitcnt lgkmcnt(10)
	v_mfma_f32_32x32x16_bf16 v[96:111], v[148:151], v[132:135], v[96:111]
	s_waitcnt lgkmcnt(9)
	v_mfma_f32_32x32x16_bf16 v[96:111], v[152:155], v[136:139], v[96:111]
	s_waitcnt lgkmcnt(8)
	v_mfma_f32_32x32x16_bf16 v[96:111], v[156:159], v[140:143], v[96:111]
	ds_read_b128 v[156:159], v251 offset:57344
	ds_read_b128 v[152:155], v252 offset:57344
	ds_read_b128 v[144:147], v198 offset:57344
	ds_read_b128 v[148:151], v199 offset:57344
	v_exp_f32_e32 v207, v112
	v_exp_f32_e32 v211, v113
	v_exp_f32_e32 v209, v114
	v_exp_f32_e32 v215, v115
	v_max3_f32 v194, v112, v113, v114
	v_pk_add_f32 v[112:113], v[206:207], v[192:193]
	v_exp_f32_e32 v213, v116
	v_pk_add_f32 v[112:113], v[210:211], v[112:113]
	v_exp_f32_e32 v219, v117
	v_pk_add_f32 v[112:113], v[208:209], v[112:113]
	v_exp_f32_e32 v217, v118
	v_pk_add_f32 v[112:113], v[214:215], v[112:113]
	v_exp_f32_e32 v223, v119
	v_exp_f32_e32 v221, v120
	v_pk_add_f32 v[112:113], v[212:213], v[112:113]
	v_exp_f32_e32 v227, v121
	v_pk_add_f32 v[112:113], v[218:219], v[112:113]
	v_exp_f32_e32 v225, v122
	v_pk_add_f32 v[112:113], v[216:217], v[112:113]
	v_exp_f32_e32 v229, v123
	v_pk_add_f32 v[112:113], v[222:223], v[112:113]
	v_exp_f32_e32 v231, v124
	v_pk_add_f32 v[112:113], v[220:221], v[112:113]
	v_exp_f32_e32 v235, v125
	v_pk_add_f32 v[112:113], v[226:227], v[112:113]
	v_exp_f32_e32 v233, v126
	v_pk_add_f32 v[112:113], v[224:225], v[112:113]
	v_exp_f32_e32 v203, v127
	v_pk_add_f32 v[112:113], v[228:229], v[112:113]
	v_max3_f32 v195, v115, v116, v117
	v_cvt_pk_bf16_f32 v114, v213, v219
	v_pk_add_f32 v[112:113], v[230:231], v[112:113]
	v_cvt_pk_bf16_f32 v115, v217, v223
	v_pk_add_f32 v[112:113], v[234:235], v[112:113]
	s_add_i32 s20, 0, 0x1c000
	v_pk_add_f32 v[112:113], v[232:233], v[112:113]
	v_max3_f32 v194, v194, v118, v119
	v_cvt_pk_bf16_f32 v116, v221, v227
	v_pk_add_f32 v[204:205], v[202:203], v[112:113]
	v_cvt_pk_bf16_f32 v112, v207, v211
	v_cvt_pk_bf16_f32 v113, v209, v215
	v_cvt_pk_bf16_f32 v117, v225, v229
	v_cvt_pk_bf16_f32 v118, v231, v235
	s_waitcnt lgkmcnt(11)
	v_mfma_f32_32x32x16_bf16 v[48:63], v[188:191], v[112:115], v[48:63]
	v_cvt_pk_bf16_f32 v119, v233, v203
	v_max3_f32 v194, v194, v122, v123
	v_max3_f32 v195, v195, v120, v121
	s_nop 0
	v_max3_f32 v194, v194, v126, v127
	v_max3_f32 v195, v195, v124, v125
	s_waitcnt lgkmcnt(10)
	v_mfma_f32_32x32x16_bf16 v[32:47], v[184:187], v[112:115], v[32:47]
	v_max3_f32 v194, v201, v194, v195
	s_waitcnt lgkmcnt(7)
	v_mfma_f32_32x32x16_bf16 v[16:31], v[180:183], v[112:115], v[16:31]
	s_waitcnt lgkmcnt(6)
	v_mfma_f32_32x32x16_bf16 v[0:15], v[176:179], v[112:115], v[0:15]
	v_add_u32_e32 v112, s20, v250
	v_add_u32_e32 v113, s20, v249
	v_mfma_f32_32x32x16_bf16 v[48:63], v[172:175], v[116:119], v[48:63]
	ds_read_b128 v[174:177], v112
	ds_read_b128 v[206:209], v113
	ds_read_b128 v[178:181], v112 offset:4096
	ds_read_b128 v[210:213], v113 offset:4096
	ds_read_b128 v[182:185], v112 offset:8192
	ds_read_b128 v[214:217], v113 offset:8192
	ds_read_b128 v[186:189], v112 offset:12288
	ds_read_b128 v[218:221], v113 offset:12288
	v_mfma_f32_32x32x16_bf16 v[32:47], v[168:171], v[116:119], v[32:47]
	s_waitcnt lgkmcnt(13)
	v_mfma_f32_32x32x16_bf16 v[16:31], v[160:163], v[116:119], v[16:31]
	s_waitcnt lgkmcnt(12)
	v_mfma_f32_32x32x16_bf16 v[0:15], v[164:167], v[116:119], v[0:15]
	s_setprio 1
	s_waitcnt lgkmcnt(11)
	v_mfma_f32_32x32x16_bf16 v[112:127], v[156:159], v[128:131], v[80:95]
	ds_read_b128 v[222:225], v251
	ds_read_b128 v[226:229], v252
	ds_read_b128 v[230:233], v198
	ds_read_b128 v[234:237], v199
	s_waitcnt lgkmcnt(14)
	v_mfma_f32_32x32x16_bf16 v[112:127], v[152:155], v[132:135], v[112:127]
	s_waitcnt lgkmcnt(13)
	v_mfma_f32_32x32x16_bf16 v[112:127], v[144:147], v[136:139], v[112:127]
	s_waitcnt lgkmcnt(12)
	v_mfma_f32_32x32x16_bf16 v[112:127], v[148:151], v[140:143], v[112:127]
	v_exp_f32_e32 v148, v96
	v_exp_f32_e32 v160, v97
	v_exp_f32_e32 v164, v98
	v_exp_f32_e32 v162, v99
	v_exp_f32_e32 v168, v100
	v_exp_f32_e32 v166, v101
	v_exp_f32_e32 v172, v102
	v_exp_f32_e32 v170, v103
	v_cvt_pk_bf16_f32 v144, v148, v160
	v_cvt_pk_bf16_f32 v145, v164, v162
	v_cvt_pk_bf16_f32 v146, v168, v166
	v_cvt_pk_bf16_f32 v147, v172, v170
	v_max3_f32 v96, v96, v97, v98
	v_max3_f32 v97, v99, v100, v101
	v_add_u32_e32 v100, s20, v247
	v_max3_f32 v96, v96, v102, v103
	v_max3_f32 v97, v97, v104, v105
	s_waitcnt lgkmcnt(11)
	v_mfma_f32_32x32x16_bf16 v[48:63], v[174:177], v[144:147], v[48:63]
	v_max3_f32 v96, v96, v106, v107
	v_exp_f32_e32 v176, v104
	v_exp_f32_e32 v174, v105
	v_max3_f32 v96, v96, v110, v111
	v_max3_f32 v97, v97, v108, v109
	v_add_f32_e32 v192, 0, v148
	v_max3_f32 v161, v194, v96, v97
	s_waitcnt lgkmcnt(9)
	v_mfma_f32_32x32x16_bf16 v[32:47], v[178:181], v[144:147], v[32:47]
	v_exp_f32_e32 v180, v106
	v_exp_f32_e32 v178, v107
	v_add_u32_e32 v96, s20, v248
	v_cvt_pk_bf16_f32 v238, v176, v174
	v_cvt_pk_bf16_f32 v239, v180, v178
	s_waitcnt lgkmcnt(7)
	v_mfma_f32_32x32x16_bf16 v[16:31], v[182:185], v[144:147], v[16:31]
	v_exp_f32_e32 v182, v108
	v_exp_f32_e32 v184, v109
	s_nop 0
	v_cvt_pk_bf16_f32 v240, v182, v184
	s_waitcnt lgkmcnt(5)
	v_mfma_f32_32x32x16_bf16 v[0:15], v[186:189], v[144:147], v[0:15]
	v_exp_f32_e32 v188, v110
	v_exp_f32_e32 v186, v111
	ds_read_b128 v[156:159], v96
	ds_read_b128 v[152:155], v96 offset:4096
	ds_read_b128 v[108:111], v100
	ds_read_b128 v[104:107], v100 offset:4096
	ds_read_b128 v[148:151], v96 offset:8192
	ds_read_b128 v[144:147], v96 offset:12288
	ds_read_b128 v[96:99], v100 offset:8192
	ds_read_b128 v[100:103], v100 offset:12288
	v_cvt_pk_bf16_f32 v241, v188, v186
	s_nop 1
	v_mfma_f32_32x32x16_bf16 v[48:63], v[206:209], v[238:241], v[48:63]
	v_mfma_f32_32x32x16_bf16 v[32:47], v[210:213], v[238:241], v[32:47]
	v_mfma_f32_32x32x16_bf16 v[16:31], v[214:217], v[238:241], v[16:31]
	s_waitcnt lgkmcnt(12)
; #define LAS __attribute__((address_space(3)))
; DI float ex2(float x) { return __builtin_amdgcn_exp2f(x); }
; DI void attn_step32(f32x16& sc, f32x16& sn, f32x16 (&O)[4], const f32x16& negm, float& lsum, float& mrun, const bf16x8 (&qf)[4],
;                     bf16x8 (&kf)[4], const LAS unsigned char* kb_next, bool has_next, const LAS unsigned char* vb, const int (&ko)[4], int vo0, int vo1) {
;     bf16x8 vf[8];
; #pragma unroll
;     for (int cb = 0; cb < 4; ++cb) { vf[cb] = *(const LAS bf16x8*)(vb + vo0 + cb * 4096); vf[4 + cb] = *(const LAS bf16x8*)(vb + vo1 + cb * 4096); }
;     __builtin_amdgcn_sched_barrier(0);
;     sn = negm;
; #pragma unroll
;     for (int ds = 0; ds < 4; ++ds) sn = MFMA32(kf[ds], qf[ds], sn);
;     if (has_next) {
; #pragma unroll
;         for (int ds = 0; ds < 4; ++ds) kf[ds] = *(const LAS bf16x8*)(kb_next + ko[ds]);
;     }
;     __builtin_amdgcn_sched_barrier(0);
;     float mx = max3f(sc[0], sc[1], sc[2]), my = max3f(sc[3], sc[4], sc[5]);
;     mx = max3f(mx, sc[6], sc[7]); my = max3f(my, sc[8], sc[9]); mx = max3f(mx, sc[10], sc[11]); my = max3f(my, sc[12], sc[13]); mx = max3f(mx, sc[14], sc[15]);
;     mrun = max3f(mrun, mx, my);
;     float ps = 0.f;
; #pragma unroll
;     for (int i = 0; i < 16; ++i) { sc[i] = ex2(sc[i]); ps += sc[i]; }
;     lsum += ps;
;     u32x4 w0, w1;
;     w0.x = pk2(sc[0], sc[1]); w0.y = pk2(sc[2], sc[3]); w0.z = pk2(sc[4], sc[5]); w0.w = pk2(sc[6], sc[7]);
;     w1.x = pk2(sc[8], sc[9]); w1.y = pk2(sc[10], sc[11]); w1.z = pk2(sc[12], sc[13]); w1.w = pk2(sc[14], sc[15]);
;     const bf16x8 pf0 = __builtin_bit_cast(bf16x8, w0), pf1 = __builtin_bit_cast(bf16x8, w1);
; #pragma unroll
;     for (int cb = 0; cb < 4; ++cb) O[cb] = MFMA32(vf[cb], pf0, O[cb]);
; #pragma unroll
;     for (int cb = 0; cb < 4; ++cb) O[cb] = MFMA32(vf[4 + cb], pf1, O[cb]);
; }
; DI void attn_renorm(f32x16& spend, f32x16 (&O)[4], f32x16& negm, float& mref, float& lsum, float& mrun) {
;     constexpr float THR = 6.0f;
;     const float mx = swap_max(mrun);
;     if (__any(mx > THR)) {
;         const float dl = fmaxf(mx, 0.f), alpha = ex2(-dl);
;         mref += dl; lsum *= alpha;
; #pragma unroll
;         for (int cb = 0; cb < 4; ++cb) O[cb] = O[cb] * alpha;
; #pragma unroll
;         for (int i = 0; i < 16; ++i) { spend[i] -= dl; negm[i] = -mref; }
;     }
;     mrun = -1.0e30f;
; }
	v_mfma_f32_32x32x16_bf16 v[0:15], v[218:221], v[238:241], v[0:15]
	s_setprio 0
	s_waitcnt lgkmcnt(11)
	v_mfma_f32_32x32x16_bf16 v[80:95], v[222:225], v[128:131], v[80:95]
	s_waitcnt lgkmcnt(10)
	v_mfma_f32_32x32x16_bf16 v[80:95], v[226:229], v[132:135], v[80:95]
	s_waitcnt lgkmcnt(9)
	v_mfma_f32_32x32x16_bf16 v[80:95], v[230:233], v[136:139], v[80:95]
	s_waitcnt lgkmcnt(8)
	v_mfma_f32_32x32x16_bf16 v[80:95], v[234:237], v[140:143], v[80:95]
	v_max3_f32 v163, v112, v113, v114
	v_max3_f32 v165, v115, v116, v117
	v_exp_f32_e32 v169, v115
	v_max3_f32 v163, v163, v118, v119
	v_max3_f32 v165, v165, v120, v121
	v_exp_f32_e32 v167, v116
	v_max3_f32 v163, v163, v122, v123
	v_max3_f32 v165, v165, v124, v125
	v_exp_f32_e32 v173, v117
	v_max3_f32 v163, v163, v126, v127
	v_exp_f32_e32 v171, v118
	v_max3_f32 v190, v161, v163, v165
	v_exp_f32_e32 v161, v112
	v_exp_f32_e32 v165, v113
	v_exp_f32_e32 v163, v114
	v_exp_f32_e32 v177, v119
	v_pk_add_f32 v[112:113], v[160:161], v[192:193]
	v_exp_f32_e32 v175, v120
	v_pk_add_f32 v[112:113], v[164:165], v[112:113]
	v_exp_f32_e32 v181, v121
	v_pk_add_f32 v[112:113], v[162:163], v[112:113]
	v_exp_f32_e32 v179, v122
	v_pk_add_f32 v[112:113], v[168:169], v[112:113]
	v_exp_f32_e32 v183, v123
	v_pk_add_f32 v[112:113], v[166:167], v[112:113]
	v_exp_f32_e32 v185, v124
	v_pk_add_f32 v[112:113], v[172:173], v[112:113]
	v_exp_f32_e32 v189, v125
	v_pk_add_f32 v[112:113], v[170:171], v[112:113]
	v_exp_f32_e32 v187, v126
	v_pk_add_f32 v[112:113], v[176:177], v[112:113]
	v_exp_f32_e32 v119, v127
	v_pk_add_f32 v[112:113], v[174:175], v[112:113]
	v_pk_add_f32 v[114:115], v[204:205], v[204:205] op_sel:[0,1] op_sel_hi:[1,0]
	v_pk_add_f32 v[112:113], v[180:181], v[112:113]
	v_mov_b32_e32 v115, v119
	v_pk_add_f32 v[112:113], v[178:179], v[112:113]
	v_cvt_pk_bf16_f32 v116, v175, v181
	v_pk_add_f32 v[112:113], v[182:183], v[112:113]
	v_cvt_pk_bf16_f32 v117, v179, v183
	v_pk_add_f32 v[112:113], v[184:185], v[112:113]
	v_cvt_pk_bf16_f32 v118, v185, v189
	v_pk_add_f32 v[112:113], v[188:189], v[112:113]
	v_cvt_pk_bf16_f32 v119, v187, v119
	v_pk_add_f32 v[112:113], v[186:187], v[112:113]
	s_nop 0
	v_pk_add_f32 v[112:113], v[114:115], v[112:113]
	v_cvt_pk_bf16_f32 v114, v167, v173
	v_add_f32_e32 v176, v112, v113
	v_cvt_pk_bf16_f32 v112, v161, v165
	v_cvt_pk_bf16_f32 v113, v163, v169
	v_cvt_pk_bf16_f32 v115, v171, v177
	s_waitcnt lgkmcnt(7)
	s_nop 0
	v_mfma_f32_32x32x16_bf16 v[48:63], v[156:159], v[112:115], v[48:63]
	s_waitcnt lgkmcnt(6)
	v_mfma_f32_32x32x16_bf16 v[32:47], v[152:155], v[112:115], v[32:47]
	s_waitcnt lgkmcnt(3)
	v_mfma_f32_32x32x16_bf16 v[16:31], v[148:151], v[112:115], v[16:31]
	s_waitcnt lgkmcnt(2)
	v_mfma_f32_32x32x16_bf16 v[0:15], v[144:147], v[112:115], v[0:15]
	v_mfma_f32_32x32x16_bf16 v[48:63], v[108:111], v[116:119], v[48:63]
	v_mfma_f32_32x32x16_bf16 v[32:47], v[104:107], v[116:119], v[32:47]
	s_waitcnt lgkmcnt(1)
	v_mfma_f32_32x32x16_bf16 v[16:31], v[96:99], v[116:119], v[16:31]
	v_mov_b32_e32 v96, v190
	s_nop 1
	v_permlane32_swap_b32_e32 v190, v96
	v_max_f32_e32 v96, v96, v96
	v_max_f32_e32 v97, v190, v190
	v_max_f32_e32 v96, v97, v96
	v_cmp_lt_f32_e32 vcc, s95, v96
	s_waitcnt lgkmcnt(0)
	v_mfma_f32_32x32x16_bf16 v[0:15], v[100:103], v[116:119], v[0:15]
	s_cbranch_vccz .LBB0_289
	v_max_f32_e32 v64, v96, v96
	v_max_f32_e32 v65, 0, v64
	v_exp_f32_e64 v64, -v65
	v_add_f32_e32 v200, v200, v65
	v_sub_f32_e32 v95, v95, v65
	v_sub_f32_e32 v94, v94, v65
	v_mul_f32_e32 v176, v176, v64
	v_pk_mul_f32 v[62:63], v[62:63], v[64:65] op_sel_hi:[1,0]
	v_pk_mul_f32 v[60:61], v[60:61], v[64:65] op_sel_hi:[1,0]
	v_pk_mul_f32 v[58:59], v[58:59], v[64:65] op_sel_hi:[1,0]
	v_pk_mul_f32 v[56:57], v[56:57], v[64:65] op_sel_hi:[1,0]
	v_pk_mul_f32 v[54:55], v[54:55], v[64:65] op_sel_hi:[1,0]
	v_pk_mul_f32 v[52:53], v[52:53], v[64:65] op_sel_hi:[1,0]
	v_pk_mul_f32 v[50:51], v[50:51], v[64:65] op_sel_hi:[1,0]
	v_pk_mul_f32 v[48:49], v[48:49], v[64:65] op_sel_hi:[1,0]
	v_pk_mul_f32 v[46:47], v[46:47], v[64:65] op_sel_hi:[1,0]
	v_pk_mul_f32 v[44:45], v[44:45], v[64:65] op_sel_hi:[1,0]
	v_pk_mul_f32 v[42:43], v[42:43], v[64:65] op_sel_hi:[1,0]
	v_pk_mul_f32 v[40:41], v[40:41], v[64:65] op_sel_hi:[1,0]
	v_pk_mul_f32 v[38:39], v[38:39], v[64:65] op_sel_hi:[1,0]
	v_pk_mul_f32 v[36:37], v[36:37], v[64:65] op_sel_hi:[1,0]
	v_pk_mul_f32 v[34:35], v[34:35], v[64:65] op_sel_hi:[1,0]
	v_pk_mul_f32 v[32:33], v[32:33], v[64:65] op_sel_hi:[1,0]
	v_pk_mul_f32 v[30:31], v[30:31], v[64:65] op_sel_hi:[1,0]
	v_pk_mul_f32 v[28:29], v[28:29], v[64:65] op_sel_hi:[1,0]
	v_pk_mul_f32 v[26:27], v[26:27], v[64:65] op_sel_hi:[1,0]
	v_pk_mul_f32 v[24:25], v[24:25], v[64:65] op_sel_hi:[1,0]
	v_pk_mul_f32 v[22:23], v[22:23], v[64:65] op_sel_hi:[1,0]
	v_pk_mul_f32 v[20:21], v[20:21], v[64:65] op_sel_hi:[1,0]
	v_pk_mul_f32 v[18:19], v[18:19], v[64:65] op_sel_hi:[1,0]
	v_pk_mul_f32 v[16:17], v[16:17], v[64:65] op_sel_hi:[1,0]
	v_pk_mul_f32 v[14:15], v[14:15], v[64:65] op_sel_hi:[1,0]
	v_pk_mul_f32 v[12:13], v[12:13], v[64:65] op_sel_hi:[1,0]
	v_pk_mul_f32 v[10:11], v[10:11], v[64:65] op_sel_hi:[1,0]
	v_pk_mul_f32 v[8:9], v[8:9], v[64:65] op_sel_hi:[1,0]
	v_pk_mul_f32 v[6:7], v[6:7], v[64:65] op_sel_hi:[1,0]
	v_pk_mul_f32 v[4:5], v[4:5], v[64:65] op_sel_hi:[1,0]
	v_pk_mul_f32 v[2:3], v[2:3], v[64:65] op_sel_hi:[1,0]
	v_pk_mul_f32 v[0:1], v[0:1], v[64:65] op_sel_hi:[1,0]
	v_xor_b32_e32 v64, 0x80000000, v200
	v_sub_f32_e32 v93, v93, v65
	v_sub_f32_e32 v92, v92, v65
	v_sub_f32_e32 v91, v91, v65
	v_sub_f32_e32 v90, v90, v65
	v_sub_f32_e32 v89, v89, v65
	v_sub_f32_e32 v88, v88, v65
	v_sub_f32_e32 v87, v87, v65
	v_sub_f32_e32 v86, v86, v65
	v_sub_f32_e32 v85, v85, v65
	v_sub_f32_e32 v84, v84, v65
	v_sub_f32_e32 v83, v83, v65
	v_sub_f32_e32 v82, v82, v65
	v_sub_f32_e32 v81, v81, v65
	v_sub_f32_e32 v80, v80, v65
	v_mov_b32_e32 v65, v64
	v_mov_b32_e32 v66, v64
	v_mov_b32_e32 v67, v64
	v_mov_b32_e32 v68, v64
	v_mov_b32_e32 v69, v64
	v_mov_b32_e32 v70, v64
	v_mov_b32_e32 v71, v64
	v_mov_b32_e32 v72, v64
	v_mov_b32_e32 v73, v64
	v_mov_b32_e32 v74, v64
	v_mov_b32_e32 v75, v64
	v_mov_b32_e32 v76, v64
	v_mov_b32_e32 v77, v64
	v_mov_b32_e32 v78, v64
	v_mov_b32_e32 v79, v64
	s_branch .LBB0_289
